# chain-ordered MFMA pairs in GEMM MMA blocks + nt hint on FFN-up ACT stores
# speedup vs baseline: 1.0126x; 1.0003x over previous
.LBB0_1485:
	s_waitcnt lgkmcnt(0)
	s_barrier
	v_lshl_add_u32 v138, v238, 2, s0
	ds_read_b128 v[188:191], v138
	ds_read_b128 v[208:211], v138 offset:16
	ds_read_b128 v[214:217], v138 offset:512
	ds_read_b128 v[230:233], v138 offset:528
	v_lshl_or_b32 v207, v239, 2, s68
	v_cmp_ne_u32_e32 vcc, 0, v207
	s_waitcnt lgkmcnt(0)
	v_mov_b32_dpp v208, v168 row_shr:1 row_mask:0xf bank_mask:0xf
	v_mov_b32_dpp v188, v184 row_shr:1 row_mask:0xf bank_mask:0xf
	v_mov_b32_dpp v189, v185 row_shr:1 row_mask:0xf bank_mask:0xf
	v_mov_b32_dpp v190, v186 row_shr:1 row_mask:0xf bank_mask:0xf
	v_mov_b32_dpp v191, v187 row_shr:1 row_mask:0xf bank_mask:0xf
	v_pk_mul_f32 v[138:139], v[54:55], v[190:191]
	v_pk_mul_f32 v[188:189], v[52:53], v[188:189]
	v_pk_fma_f32 v[138:139], v[178:179], v[62:63], v[138:139]
	v_pk_fma_f32 v[188:189], v[176:177], v[60:61], v[188:189]
	v_pk_fma_f32 v[138:139], v[162:163], v[58:59], v[138:139]
	v_pk_fma_f32 v[188:189], v[160:161], v[56:57], v[188:189]
	v_mov_b32_dpp v214, v200 row_shr:1 row_mask:0xf bank_mask:0xf
	v_mov_b32_dpp v215, v201 row_shr:1 row_mask:0xf bank_mask:0xf
	v_pk_mul_f32 v[190:191], v[40:41], v[214:215]
	v_exp_f32_e32 v204, v188
	v_exp_f32_e32 v214, v138
	v_exp_f32_e32 v215, v139
	v_exp_f32_e32 v205, v189
	v_mov_b32_dpp v216, v202 row_shr:1 row_mask:0xf bank_mask:0xf
	v_mov_b32_dpp v217, v203 row_shr:1 row_mask:0xf bank_mask:0xf
	v_pk_add_f32 v[214:215], v[214:215], 1.0 op_sel_hi:[1,0]
	v_pk_add_f32 v[204:205], v[204:205], 1.0 op_sel_hi:[1,0]
	v_rcp_f32_e32 v214, v214
	v_rcp_f32_e32 v204, v204
	v_rcp_f32_e32 v205, v205
	v_rcp_f32_e32 v215, v215
	v_pk_mul_f32 v[194:195], v[42:43], v[216:217]
	v_pk_fma_f32 v[190:191], v[196:197], v[44:45], v[190:191]
	v_pk_fma_f32 v[194:195], v[198:199], v[46:47], v[194:195]
	v_pk_fma_f32 v[190:191], v[132:133], v[48:49], v[190:191]
	v_pk_fma_f32 v[194:195], v[134:135], v[50:51], v[194:195]
	v_pk_mul_f32 v[188:189], v[188:189], v[204:205]
	v_pk_mul_f32 v[138:139], v[138:139], v[214:215]
	v_mov_b32_dpp v209, v169 row_shr:1 row_mask:0xf bank_mask:0xf
	v_pk_mul_f32 v[138:139], v[194:195], v[138:139]
	v_pk_mul_f32 v[188:189], v[190:191], v[188:189]
	v_mov_b32_dpp v210, v170 row_shr:1 row_mask:0xf bank_mask:0xf
	v_mov_b32_dpp v211, v171 row_shr:1 row_mask:0xf bank_mask:0xf
	v_pk_mul_f32 v[190:191], v[28:29], v[208:209]
	v_cvt_pk_bf16_f32 v188, v188, v189
	v_cvt_pk_bf16_f32 v189, v138, v139
	v_pk_mul_f32 v[138:139], v[30:31], v[210:211]
	v_pk_fma_f32 v[190:191], v[164:165], v[36:37], v[190:191]
	v_pk_fma_f32 v[138:139], v[166:167], v[38:39], v[138:139]
	v_pk_fma_f32 v[190:191], v[156:157], v[32:33], v[190:191]
	v_pk_fma_f32 v[138:139], v[158:159], v[34:35], v[138:139]
	v_exp_f32_e32 v208, v190
	v_exp_f32_e32 v209, v191
	v_exp_f32_e32 v210, v138
	v_exp_f32_e32 v211, v139
	v_mov_b32_dpp v230, v180 row_shr:1 row_mask:0xf bank_mask:0xf
	v_pk_add_f32 v[208:209], v[208:209], 1.0 op_sel_hi:[1,0]
	v_mov_b32_dpp v231, v181 row_shr:1 row_mask:0xf bank_mask:0xf
	v_pk_add_f32 v[210:211], v[210:211], 1.0 op_sel_hi:[1,0]
	v_rcp_f32_e32 v208, v208
	v_rcp_f32_e32 v209, v209
	v_rcp_f32_e32 v210, v210
	v_rcp_f32_e32 v211, v211
	v_mov_b32_dpp v232, v182 row_shr:1 row_mask:0xf bank_mask:0xf
	v_mov_b32_dpp v233, v183 row_shr:1 row_mask:0xf bank_mask:0xf
	v_pk_mul_f32 v[194:195], v[16:17], v[230:231]
	v_pk_mul_f32 v[204:205], v[18:19], v[232:233]
	v_pk_fma_f32 v[194:195], v[172:173], v[20:21], v[194:195]
	v_pk_fma_f32 v[204:205], v[174:175], v[22:23], v[204:205]
	v_pk_fma_f32 v[194:195], v[128:129], v[24:25], v[194:195]
	v_pk_mul_f32 v[190:191], v[190:191], v[208:209]
	v_pk_fma_f32 v[204:205], v[130:131], v[26:27], v[204:205]
	v_pk_mul_f32 v[138:139], v[138:139], v[210:211]
	v_pk_mul_f32 v[190:191], v[194:195], v[190:191]
	v_add_u32_e32 v208, s8, v207
	v_pk_mul_f32 v[138:139], v[204:205], v[138:139]
	v_cvt_pk_bf16_f32 v190, v190, v191
	s_nop 0
	v_cvt_pk_bf16_f32 v191, v138, v139
	s_and_saveexec_b64 s[2:3], vcc
	s_cbranch_execz .LBB0_1487
	v_mov_b64_e32 v[138:139], s[42:43]
	v_mad_i64_i32 v[138:139], s[12:13], v208, s22, v[138:139]
	v_lshl_add_u64 v[138:139], v[192:193], 1, v[138:139]
	global_store_dwordx4 v[138:139], v[188:191], off nt
.LBB0_1487:
	s_or_b64 exec, exec, s[2:3]
	v_pk_fma_f32 v[194:195], v[110:111], v[206:207], v[154:155] op_sel_hi:[1,0,1]
	v_pk_fma_f32 v[138:139], v[106:107], v[206:207], v[150:151] op_sel_hi:[1,0,1]
	v_pk_fma_f32 v[106:107], v[98:99], v[206:207], v[142:143] op_sel_hi:[1,0,1]
	v_pk_fma_f32 v[110:111], v[96:97], v[206:207], v[140:141] op_sel_hi:[1,0,1]
	v_pk_mul_f32 v[96:97], v[162:163], v[62:63]
	v_pk_mul_f32 v[98:99], v[160:161], v[60:61]
	v_pk_fma_f32 v[204:205], v[108:109], v[206:207], v[152:153] op_sel_hi:[1,0,1]
	v_pk_fma_f32 v[96:97], v[178:179], v[54:55], v[96:97]
	v_pk_fma_f32 v[98:99], v[176:177], v[52:53], v[98:99]
	v_pk_fma_f32 v[96:97], v[194:195], v[58:59], v[96:97]
	v_pk_fma_f32 v[98:99], v[204:205], v[56:57], v[98:99]
	v_exp_f32_e32 v210, v96
	v_exp_f32_e32 v108, v98
	v_exp_f32_e32 v109, v99
	v_exp_f32_e32 v211, v97
	v_pk_fma_f32 v[188:189], v[104:105], v[206:207], v[148:149] op_sel_hi:[1,0,1]
	v_pk_fma_f32 v[104:105], v[102:103], v[206:207], v[146:147] op_sel_hi:[1,0,1]
	v_pk_add_f32 v[108:109], v[108:109], 1.0 op_sel_hi:[1,0]
	v_pk_add_f32 v[210:211], v[210:211], 1.0 op_sel_hi:[1,0]
	v_rcp_f32_e32 v108, v108
	v_rcp_f32_e32 v109, v109
	v_rcp_f32_e32 v210, v210
	v_rcp_f32_e32 v211, v211
	v_pk_fma_f32 v[190:191], v[100:101], v[206:207], v[144:145] op_sel_hi:[1,0,1]
	v_pk_mul_f32 v[100:101], v[134:135], v[46:47]
	v_pk_mul_f32 v[102:103], v[132:133], v[44:45]
	v_pk_fma_f32 v[100:101], v[198:199], v[42:43], v[100:101]
	v_pk_fma_f32 v[102:103], v[196:197], v[40:41], v[102:103]
	v_pk_fma_f32 v[100:101], v[104:105], v[50:51], v[100:101]
	v_pk_fma_f32 v[102:103], v[190:191], v[48:49], v[102:103]
	v_pk_mul_f32 v[96:97], v[96:97], v[210:211]
	v_pk_mul_f32 v[98:99], v[98:99], v[108:109]
	v_pk_mul_f32 v[100:101], v[100:101], v[96:97]
	v_pk_mul_f32 v[96:97], v[102:103], v[98:99]
	v_pk_mul_f32 v[98:99], v[158:159], v[38:39]
	v_cvt_pk_bf16_f32 v96, v96, v97
	v_cvt_pk_bf16_f32 v97, v100, v101
	v_pk_mul_f32 v[100:101], v[156:157], v[36:37]
	v_pk_fma_f32 v[98:99], v[166:167], v[30:31], v[98:99]
	v_pk_fma_f32 v[100:101], v[164:165], v[28:29], v[100:101]
	v_pk_fma_f32 v[98:99], v[138:139], v[34:35], v[98:99]
	v_pk_fma_f32 v[100:101], v[188:189], v[32:33], v[100:101]
	v_exp_f32_e32 v214, v98
	v_exp_f32_e32 v210, v100
	v_exp_f32_e32 v211, v101
	v_exp_f32_e32 v215, v99
	v_pk_mul_f32 v[234:235], v[194:195], v[62:63]
	v_pk_mul_f32 v[240:241], v[204:205], v[60:61]
	v_pk_fma_f32 v[162:163], v[162:163], v[54:55], v[234:235]
	v_pk_fma_f32 v[160:161], v[160:161], v[52:53], v[240:241]
	v_pk_fma_f32 v[162:163], v[186:187], v[58:59], v[162:163]
	v_pk_fma_f32 v[160:161], v[184:185], v[56:57], v[160:161]
	v_pk_mul_f32 v[234:235], v[104:105], v[46:47]
	v_pk_mul_f32 v[240:241], v[190:191], v[44:45]
	v_pk_fma_f32 v[134:135], v[134:135], v[42:43], v[234:235]
	v_pk_fma_f32 v[132:133], v[132:133], v[40:41], v[240:241]
	v_exp_f32_e32 v234, v160
	v_exp_f32_e32 v235, v161
	v_exp_f32_e32 v240, v162
	v_exp_f32_e32 v241, v163
	v_pk_add_f32 v[214:215], v[214:215], 1.0 op_sel_hi:[1,0]
	v_pk_add_f32 v[210:211], v[210:211], 1.0 op_sel_hi:[1,0]
	v_rcp_f32_e32 v214, v214
	v_rcp_f32_e32 v210, v210
	v_rcp_f32_e32 v211, v211
	v_rcp_f32_e32 v215, v215
	v_pk_mul_f32 v[102:103], v[130:131], v[22:23]
	v_pk_mul_f32 v[108:109], v[128:129], v[20:21]
	v_pk_add_f32 v[240:241], v[240:241], 1.0 op_sel_hi:[1,0]
	v_pk_add_f32 v[234:235], v[234:235], 1.0 op_sel_hi:[1,0]
	v_pk_fma_f32 v[102:103], v[174:175], v[18:19], v[102:103]
	v_pk_fma_f32 v[108:109], v[172:173], v[16:17], v[108:109]
	v_rcp_f32_e32 v234, v234
	v_rcp_f32_e32 v235, v235
	v_rcp_f32_e32 v240, v240
	v_rcp_f32_e32 v241, v241
	v_pk_fma_f32 v[102:103], v[106:107], v[26:27], v[102:103]
	v_pk_fma_f32 v[108:109], v[110:111], v[24:25], v[108:109]
	v_pk_mul_f32 v[98:99], v[98:99], v[214:215]
	v_pk_mul_f32 v[100:101], v[100:101], v[210:211]
	v_pk_mul_f32 v[102:103], v[102:103], v[98:99]
	v_pk_mul_f32 v[98:99], v[108:109], v[100:101]
	v_add_u32_e32 v100, 1, v208
	v_mov_b64_e32 v[210:211], s[42:43]
	v_mad_i64_i32 v[100:101], s[2:3], v100, s22, v[210:211]
	v_lshlrev_b64 v[108:109], 1, v[192:193]
	v_lshl_add_u64 v[100:101], v[100:101], 0, v[108:109]
	v_pk_fma_f32 v[134:135], v[202:203], v[50:51], v[134:135]
	v_pk_fma_f32 v[132:133], v[200:201], v[48:49], v[132:133]
	v_pk_mul_f32 v[162:163], v[162:163], v[240:241]
	v_pk_mul_f32 v[160:161], v[160:161], v[234:235]
	v_lshl_add_u32 v209, v238, 2, s1
	v_cvt_pk_bf16_f32 v98, v98, v99
	v_cvt_pk_bf16_f32 v99, v102, v103
	global_store_dwordx4 v[100:101], v[96:99], off nt
	v_pk_mul_f32 v[134:135], v[134:135], v[162:163]
	v_pk_mul_f32 v[132:133], v[132:133], v[160:161]
	v_pk_mul_f32 v[160:161], v[188:189], v[36:37]
	ds_read_b128 v[214:217], v209
	ds_read_b128 v[100:103], v209 offset:16
	ds_read_b128 v[230:233], v209 offset:512
	ds_read_b128 v[96:99], v209 offset:528
	v_cvt_pk_bf16_f32 v132, v132, v133
	v_cvt_pk_bf16_f32 v133, v134, v135
	v_pk_mul_f32 v[134:135], v[138:139], v[38:39]
	v_pk_fma_f32 v[156:157], v[156:157], v[28:29], v[160:161]
	v_pk_fma_f32 v[134:135], v[158:159], v[30:31], v[134:135]
	v_pk_fma_f32 v[156:157], v[168:169], v[32:33], v[156:157]
	v_pk_mul_f32 v[158:159], v[106:107], v[22:23]
	v_pk_fma_f32 v[134:135], v[170:171], v[34:35], v[134:135]
	v_pk_mul_f32 v[160:161], v[110:111], v[20:21]
	v_pk_fma_f32 v[130:131], v[130:131], v[18:19], v[158:159]
	v_exp_f32_e32 v158, v156
	v_exp_f32_e32 v159, v157
	v_pk_fma_f32 v[128:129], v[128:129], v[16:17], v[160:161]
	v_exp_f32_e32 v160, v134
	v_exp_f32_e32 v161, v135
	v_pk_add_f32 v[158:159], v[158:159], 1.0 op_sel_hi:[1,0]
	v_pk_fma_f32 v[128:129], v[180:181], v[24:25], v[128:129]
	v_rcp_f32_e32 v158, v158
	v_pk_add_f32 v[160:161], v[160:161], 1.0 op_sel_hi:[1,0]
	v_rcp_f32_e32 v159, v159
	v_rcp_f32_e32 v160, v160
	v_rcp_f32_e32 v161, v161
	v_pk_fma_f32 v[130:131], v[182:183], v[26:27], v[130:131]
	v_pk_mul_f32 v[156:157], v[156:157], v[158:159]
	s_waitcnt lgkmcnt(0)
	v_mov_b32_dpp v214, v176 row_shl:1 row_mask:0xf bank_mask:0xf
	v_pk_mul_f32 v[134:135], v[134:135], v[160:161]
	v_pk_mul_f32 v[128:129], v[128:129], v[156:157]
	v_pk_mul_f32 v[130:131], v[130:131], v[134:135]
	v_cvt_pk_bf16_f32 v134, v128, v129
	v_add_u32_e32 v128, 2, v208
	v_mad_i64_i32 v[128:129], s[2:3], v128, s22, v[210:211]
	v_lshl_add_u64 v[128:129], v[128:129], 0, v[108:109]
	v_cvt_pk_bf16_f32 v135, v130, v131
	global_store_dwordx4 v[128:129], v[132:135], off nt
	v_pk_mul_f32 v[128:129], v[186:187], v[62:63]
	v_pk_mul_f32 v[130:131], v[184:185], v[60:61]
	v_mov_b32_dpp v215, v177 row_shl:1 row_mask:0xf bank_mask:0xf
	v_mov_b32_dpp v216, v178 row_shl:1 row_mask:0xf bank_mask:0xf
	v_mov_b32_dpp v217, v179 row_shl:1 row_mask:0xf bank_mask:0xf
	v_pk_fma_f32 v[128:129], v[194:195], v[54:55], v[128:129]
	v_pk_fma_f32 v[130:131], v[204:205], v[52:53], v[130:131]
	v_pk_fma_f32 v[128:129], v[58:59], v[216:217], v[128:129]
	v_pk_fma_f32 v[130:131], v[56:57], v[214:215], v[130:131]
	v_pk_mul_f32 v[132:133], v[202:203], v[46:47]
	v_pk_mul_f32 v[134:135], v[200:201], v[44:45]
	v_pk_fma_f32 v[104:105], v[104:105], v[42:43], v[132:133]
	v_pk_fma_f32 v[132:133], v[190:191], v[40:41], v[134:135]
	v_exp_f32_e32 v134, v130
	v_exp_f32_e32 v135, v131
	v_exp_f32_e32 v156, v128
	v_exp_f32_e32 v157, v129
	v_mov_b32_dpp v230, v196 row_shl:1 row_mask:0xf bank_mask:0xf
	v_pk_add_f32 v[134:135], v[134:135], 1.0 op_sel_hi:[1,0]
	v_mov_b32_dpp v231, v197 row_shl:1 row_mask:0xf bank_mask:0xf
	v_pk_add_f32 v[156:157], v[156:157], 1.0 op_sel_hi:[1,0]
	v_rcp_f32_e32 v134, v134
	v_rcp_f32_e32 v135, v135
	v_rcp_f32_e32 v156, v156
	v_rcp_f32_e32 v157, v157
	v_mov_b32_dpp v232, v198 row_shl:1 row_mask:0xf bank_mask:0xf
	v_mov_b32_dpp v233, v199 row_shl:1 row_mask:0xf bank_mask:0xf
	v_pk_fma_f32 v[104:105], v[50:51], v[232:233], v[104:105]
	v_pk_fma_f32 v[132:133], v[48:49], v[230:231], v[132:133]
	v_pk_mul_f32 v[128:129], v[128:129], v[156:157]
	v_pk_mul_f32 v[130:131], v[130:131], v[134:135]
	v_pk_mul_f32 v[128:129], v[104:105], v[128:129]
	v_pk_mul_f32 v[104:105], v[132:133], v[130:131]
	v_pk_mul_f32 v[130:131], v[168:169], v[36:37]
	v_cvt_pk_bf16_f32 v104, v104, v105
	v_cvt_pk_bf16_f32 v105, v128, v129
	v_pk_mul_f32 v[128:129], v[170:171], v[38:39]
	v_mov_b32_dpp v100, v164 row_shl:1 row_mask:0xf bank_mask:0xf
	v_mov_b32_dpp v101, v165 row_shl:1 row_mask:0xf bank_mask:0xf
	v_mov_b32_dpp v102, v166 row_shl:1 row_mask:0xf bank_mask:0xf
	v_mov_b32_dpp v103, v167 row_shl:1 row_mask:0xf bank_mask:0xf
	v_pk_fma_f32 v[128:129], v[138:139], v[30:31], v[128:129]
	v_pk_fma_f32 v[130:131], v[188:189], v[28:29], v[130:131]
	v_pk_fma_f32 v[102:103], v[34:35], v[102:103], v[128:129]
	v_pk_fma_f32 v[100:101], v[32:33], v[100:101], v[130:131]
	v_pk_mul_f32 v[128:129], v[182:183], v[22:23]
	v_pk_mul_f32 v[130:131], v[180:181], v[20:21]
	v_mov_b32_dpp v96, v172 row_shl:1 row_mask:0xf bank_mask:0xf
	v_mov_b32_dpp v97, v173 row_shl:1 row_mask:0xf bank_mask:0xf
	v_mov_b32_dpp v98, v174 row_shl:1 row_mask:0xf bank_mask:0xf
	v_mov_b32_dpp v99, v175 row_shl:1 row_mask:0xf bank_mask:0xf
	v_pk_fma_f32 v[106:107], v[106:107], v[18:19], v[128:129]
	v_pk_fma_f32 v[110:111], v[110:111], v[16:17], v[130:131]
	v_pk_fma_f32 v[98:99], v[26:27], v[98:99], v[106:107]
	v_pk_fma_f32 v[96:97], v[24:25], v[96:97], v[110:111]
	v_exp_f32_e32 v106, v100
	v_exp_f32_e32 v107, v101
	v_exp_f32_e32 v110, v102
	v_exp_f32_e32 v111, v103
	s_movk_i32 s2, 0xfc
	v_pk_add_f32 v[106:107], v[106:107], 1.0 op_sel_hi:[1,0]
	v_cmp_ne_u32_e32 vcc, s2, v207
	v_pk_add_f32 v[110:111], v[110:111], 1.0 op_sel_hi:[1,0]
	v_rcp_f32_e32 v106, v106
	v_rcp_f32_e32 v107, v107
	v_rcp_f32_e32 v110, v110
	v_rcp_f32_e32 v111, v111
	v_pk_mul_f32 v[100:101], v[100:101], v[106:107]
	s_nop 0
	v_pk_mul_f32 v[96:97], v[96:97], v[100:101]
	v_pk_mul_f32 v[102:103], v[102:103], v[110:111]
	v_cvt_pk_bf16_f32 v106, v96, v97
	s_nop 0
	v_pk_mul_f32 v[98:99], v[98:99], v[102:103]
	s_nop 0
	v_cvt_pk_bf16_f32 v107, v98, v99
	s_and_saveexec_b64 s[2:3], vcc
	s_cbranch_execz .LBB0_1489
	v_add3_u32 v98, v207, s8, 3
	v_mov_b64_e32 v[96:97], s[42:43]
	v_mad_i64_i32 v[96:97], s[8:9], v98, s22, v[96:97]
	v_lshl_add_u64 v[96:97], v[192:193], 1, v[96:97]
	global_store_dwordx4 v[96:97], v[104:107], off nt
.LBB0_1489:
	s_or_b64 exec, exec, s[2:3]
	v_lshl_add_u32 v110, v238, 2, s80
	v_pk_fma_f32 v[96:97], v[4:5], v[136:137], v[144:145] op_sel:[0,1,0]
	v_pk_fma_f32 v[100:101], v[6:7], v[136:137], v[146:147] op_sel:[0,1,0]
	ds_read_b128 v[4:7], v110
	v_pk_fma_f32 v[98:99], v[12:13], v[136:137], v[152:153] op_sel:[0,1,0]
	v_pk_fma_f32 v[102:103], v[14:15], v[136:137], v[154:155] op_sel:[0,1,0]
	v_pk_fma_f32 v[12:13], v[8:9], v[136:137], v[148:149] op_sel:[0,1,0]
	v_pk_fma_f32 v[8:9], v[0:1], v[136:137], v[140:141] op_sel:[0,1,0]
	s_waitcnt lgkmcnt(0)
	v_mov_b32_dpp v4, v84 row_shr:1 row_mask:0xf bank_mask:0xf
	v_mov_b32_dpp v5, v85 row_shr:1 row_mask:0xf bank_mask:0xf
	v_mov_b32_dpp v6, v86 row_shr:1 row_mask:0xf bank_mask:0xf
	v_mov_b32_dpp v7, v87 row_shr:1 row_mask:0xf bank_mask:0xf
	v_pk_mul_f32 v[6:7], v[54:55], v[6:7]
	v_pk_mul_f32 v[4:5], v[52:53], v[4:5]
	v_pk_fma_f32 v[6:7], v[82:83], v[62:63], v[6:7]
	v_pk_fma_f32 v[4:5], v[80:81], v[60:61], v[4:5]
	v_pk_fma_f32 v[6:7], v[102:103], v[58:59], v[6:7]
	v_pk_fma_f32 v[4:5], v[98:99], v[56:57], v[4:5]
	v_pk_fma_f32 v[14:15], v[2:3], v[136:137], v[142:143] op_sel:[0,1,0]
	ds_read_b128 v[104:107], v110 offset:16
	ds_read_b128 v[0:3], v110 offset:512
	ds_read_b128 v[128:131], v110 offset:528
	v_exp_f32_e32 v110, v4
	v_exp_f32_e32 v132, v6
	v_exp_f32_e32 v133, v7
	v_exp_f32_e32 v111, v5
	s_waitcnt lgkmcnt(0)
	v_mov_b32_dpp v0, v92 row_shr:1 row_mask:0xf bank_mask:0xf
	v_mov_b32_dpp v1, v93 row_shr:1 row_mask:0xf bank_mask:0xf
	v_pk_add_f32 v[132:133], v[132:133], 1.0 op_sel_hi:[1,0]
	v_pk_add_f32 v[110:111], v[110:111], 1.0 op_sel_hi:[1,0]
	v_rcp_f32_e32 v132, v132
	v_rcp_f32_e32 v110, v110
	v_rcp_f32_e32 v111, v111
	v_rcp_f32_e32 v133, v133
	v_mov_b32_dpp v2, v94 row_shr:1 row_mask:0xf bank_mask:0xf
	v_mov_b32_dpp v3, v95 row_shr:1 row_mask:0xf bank_mask:0xf
	v_pk_mul_f32 v[0:1], v[40:41], v[0:1]
	v_pk_mul_f32 v[2:3], v[42:43], v[2:3]
	v_pk_fma_f32 v[0:1], v[88:89], v[44:45], v[0:1]
	v_pk_fma_f32 v[2:3], v[90:91], v[46:47], v[2:3]
	v_pk_fma_f32 v[0:1], v[96:97], v[48:49], v[0:1]
	v_pk_fma_f32 v[2:3], v[100:101], v[50:51], v[2:3]
	v_pk_mul_f32 v[4:5], v[4:5], v[110:111]
	v_pk_mul_f32 v[6:7], v[6:7], v[132:133]
	v_pk_mul_f32 v[0:1], v[0:1], v[4:5]
	v_pk_mul_f32 v[2:3], v[2:3], v[6:7]
	v_mov_b32_dpp v104, v68 row_shr:1 row_mask:0xf bank_mask:0xf
	v_mov_b32_dpp v105, v69 row_shr:1 row_mask:0xf bank_mask:0xf
	v_mov_b32_dpp v106, v70 row_shr:1 row_mask:0xf bank_mask:0xf
	v_mov_b32_dpp v107, v71 row_shr:1 row_mask:0xf bank_mask:0xf
	v_cvt_pk_bf16_f32 v0, v0, v1
	v_cvt_pk_bf16_f32 v1, v2, v3
	v_pk_mul_f32 v[2:3], v[30:31], v[106:107]
	v_pk_mul_f32 v[4:5], v[28:29], v[104:105]
	v_pk_fma_f32 v[10:11], v[10:11], v[136:137], v[150:151] op_sel:[0,1,0]
	v_pk_fma_f32 v[4:5], v[64:65], v[36:37], v[4:5]
	v_pk_fma_f32 v[2:3], v[66:67], v[38:39], v[2:3]
	v_pk_fma_f32 v[4:5], v[12:13], v[32:33], v[4:5]
	v_pk_fma_f32 v[2:3], v[10:11], v[34:35], v[2:3]
	v_exp_f32_e32 v106, v4
	v_exp_f32_e32 v110, v2
	v_exp_f32_e32 v111, v3
	v_exp_f32_e32 v107, v5
	v_mov_b32_dpp v128, v76 row_shr:1 row_mask:0xf bank_mask:0xf
	v_mov_b32_dpp v129, v77 row_shr:1 row_mask:0xf bank_mask:0xf
	v_pk_add_f32 v[110:111], v[110:111], 1.0 op_sel_hi:[1,0]
	v_pk_add_f32 v[106:107], v[106:107], 1.0 op_sel_hi:[1,0]
	v_rcp_f32_e32 v110, v110
	v_rcp_f32_e32 v106, v106
	v_rcp_f32_e32 v107, v107
	v_rcp_f32_e32 v111, v111
	v_mov_b32_dpp v130, v78 row_shr:1 row_mask:0xf bank_mask:0xf
	v_mov_b32_dpp v131, v79 row_shr:1 row_mask:0xf bank_mask:0xf
	v_pk_mul_f32 v[6:7], v[16:17], v[128:129]
	v_pk_mul_f32 v[104:105], v[18:19], v[130:131]
	v_pk_fma_f32 v[6:7], v[72:73], v[20:21], v[6:7]
	v_pk_fma_f32 v[104:105], v[74:75], v[22:23], v[104:105]
	v_pk_fma_f32 v[6:7], v[8:9], v[24:25], v[6:7]
	v_pk_fma_f32 v[104:105], v[14:15], v[26:27], v[104:105]
	v_pk_mul_f32 v[4:5], v[4:5], v[106:107]
	v_pk_mul_f32 v[2:3], v[2:3], v[110:111]
	s_movk_i32 s2, 0xff80
	v_pk_mul_f32 v[104:105], v[104:105], v[2:3]
	v_pk_mul_f32 v[2:3], v[6:7], v[4:5]
	v_cmp_ne_u32_e32 vcc, s2, v207
	v_cvt_pk_bf16_f32 v2, v2, v3
	v_cvt_pk_bf16_f32 v3, v104, v105
	s_and_saveexec_b64 s[2:3], vcc
	s_cbranch_execz .LBB0_1491
	v_add_u32_e32 v6, 0x80, v208
	v_mov_b64_e32 v[4:5], s[42:43]
	v_mad_i64_i32 v[4:5], s[8:9], v6, s22, v[4:5]
	v_lshl_add_u64 v[4:5], v[192:193], 1, v[4:5]
	global_store_dwordx4 v[4:5], v[0:3], off nt
.LBB0_1491:
	s_or_b64 exec, exec, s[2:3]
	s_nop 0
	v_pk_mul_f32 v[0:1], v[102:103], v[62:63]
	v_pk_mul_f32 v[2:3], v[98:99], v[60:61]
	v_pk_fma_f32 v[0:1], v[82:83], v[54:55], v[0:1]
	v_pk_fma_f32 v[2:3], v[80:81], v[52:53], v[2:3]
	v_pk_fma_f32 v[0:1], v[126:127], v[58:59], v[0:1]
	v_pk_fma_f32 v[2:3], v[124:125], v[56:57], v[2:3]
	v_exp_f32_e32 v106, v0
	v_exp_f32_e32 v104, v2
	v_exp_f32_e32 v105, v3
	v_exp_f32_e32 v107, v1
	v_pk_mul_f32 v[4:5], v[100:101], v[46:47]
	v_pk_mul_f32 v[6:7], v[96:97], v[44:45]
	v_pk_add_f32 v[104:105], v[104:105], 1.0 op_sel_hi:[1,0]
	v_pk_add_f32 v[106:107], v[106:107], 1.0 op_sel_hi:[1,0]
	v_rcp_f32_e32 v104, v104
	v_rcp_f32_e32 v105, v105
	v_rcp_f32_e32 v106, v106
	v_rcp_f32_e32 v107, v107
	v_pk_fma_f32 v[4:5], v[90:91], v[42:43], v[4:5]
	v_pk_fma_f32 v[6:7], v[88:89], v[40:41], v[6:7]
	v_pk_fma_f32 v[4:5], v[118:119], v[50:51], v[4:5]
	v_pk_fma_f32 v[6:7], v[116:117], v[48:49], v[6:7]
	v_pk_mul_f32 v[0:1], v[0:1], v[106:107]
	v_pk_mul_f32 v[2:3], v[2:3], v[104:105]
	v_pk_mul_f32 v[4:5], v[4:5], v[0:1]
	v_pk_mul_f32 v[0:1], v[6:7], v[2:3]
	v_pk_mul_f32 v[2:3], v[10:11], v[38:39]
	v_cvt_pk_bf16_f32 v0, v0, v1
	v_cvt_pk_bf16_f32 v1, v4, v5
	v_pk_mul_f32 v[4:5], v[12:13], v[36:37]
	v_pk_fma_f32 v[2:3], v[66:67], v[30:31], v[2:3]
	v_pk_fma_f32 v[4:5], v[64:65], v[28:29], v[4:5]
	v_pk_fma_f32 v[2:3], v[122:123], v[34:35], v[2:3]
	v_pk_fma_f32 v[4:5], v[120:121], v[32:33], v[4:5]
	v_exp_f32_e32 v110, v2
	v_exp_f32_e32 v106, v4
	v_exp_f32_e32 v107, v5
	v_exp_f32_e32 v111, v3
	v_pk_mul_f32 v[6:7], v[14:15], v[22:23]
	v_pk_mul_f32 v[104:105], v[8:9], v[20:21]
	v_pk_add_f32 v[106:107], v[106:107], 1.0 op_sel_hi:[1,0]
	v_pk_add_f32 v[110:111], v[110:111], 1.0 op_sel_hi:[1,0]
	v_rcp_f32_e32 v106, v106
	v_rcp_f32_e32 v107, v107
	v_rcp_f32_e32 v110, v110
	v_rcp_f32_e32 v111, v111
	v_pk_fma_f32 v[6:7], v[74:75], v[18:19], v[6:7]
	v_pk_fma_f32 v[104:105], v[72:73], v[16:17], v[104:105]
	v_pk_fma_f32 v[6:7], v[114:115], v[26:27], v[6:7]
	v_pk_fma_f32 v[104:105], v[112:113], v[24:25], v[104:105]
	v_pk_mul_f32 v[2:3], v[2:3], v[110:111]
	v_pk_mul_f32 v[4:5], v[4:5], v[106:107]
	v_pk_mul_f32 v[6:7], v[6:7], v[2:3]
	v_pk_mul_f32 v[2:3], v[104:105], v[4:5]
	v_add_u32_e32 v4, 0x81, v208
	v_mov_b64_e32 v[110:111], s[42:43]
	v_mad_i64_i32 v[4:5], s[2:3], v4, s22, v[110:111]
	v_lshl_add_u64 v[4:5], v[4:5], 0, v[108:109]
	v_lshl_add_u32 v132, v238, 2, s87
	v_cvt_pk_bf16_f32 v2, v2, v3
	v_cvt_pk_bf16_f32 v3, v6, v7
	global_store_dwordx4 v[4:5], v[0:3], off nt
	ds_read_b128 v[104:107], v132
	ds_read_b128 v[4:7], v132 offset:16
	ds_read_b128 v[128:131], v132 offset:512
	ds_read_b128 v[0:3], v132 offset:528
	v_pk_mul_f32 v[132:133], v[126:127], v[62:63]
	v_pk_mul_f32 v[134:135], v[124:125], v[60:61]
	v_pk_fma_f32 v[102:103], v[102:103], v[54:55], v[132:133]
	v_pk_fma_f32 v[98:99], v[98:99], v[52:53], v[134:135]
	v_pk_fma_f32 v[102:103], v[86:87], v[58:59], v[102:103]
	v_pk_fma_f32 v[98:99], v[84:85], v[56:57], v[98:99]
	v_pk_mul_f32 v[132:133], v[118:119], v[46:47]
	v_pk_mul_f32 v[134:135], v[116:117], v[44:45]
	v_pk_fma_f32 v[100:101], v[100:101], v[42:43], v[132:133]
	v_pk_fma_f32 v[96:97], v[96:97], v[40:41], v[134:135]
	v_exp_f32_e32 v132, v98
	v_exp_f32_e32 v133, v99
	v_exp_f32_e32 v134, v102
	v_exp_f32_e32 v135, v103
	v_pk_fma_f32 v[100:101], v[94:95], v[50:51], v[100:101]
	v_pk_add_f32 v[132:133], v[132:133], 1.0 op_sel_hi:[1,0]
	v_pk_fma_f32 v[96:97], v[92:93], v[48:49], v[96:97]
	v_pk_add_f32 v[134:135], v[134:135], 1.0 op_sel_hi:[1,0]
	v_rcp_f32_e32 v132, v132
	v_rcp_f32_e32 v133, v133
	v_rcp_f32_e32 v134, v134
	v_rcp_f32_e32 v135, v135
	s_waitcnt lgkmcnt(0)
	v_mov_b32_dpp v104, v80 row_shl:1 row_mask:0xf bank_mask:0xf
	v_pk_mul_f32 v[98:99], v[98:99], v[132:133]
	v_mov_b32_dpp v105, v81 row_shl:1 row_mask:0xf bank_mask:0xf
	v_pk_mul_f32 v[102:103], v[102:103], v[134:135]
	v_pk_mul_f32 v[96:97], v[96:97], v[98:99]
	v_pk_mul_f32 v[100:101], v[100:101], v[102:103]
	v_cvt_pk_bf16_f32 v96, v96, v97
	v_pk_mul_f32 v[98:99], v[122:123], v[38:39]
	v_cvt_pk_bf16_f32 v97, v100, v101
	v_pk_mul_f32 v[100:101], v[120:121], v[36:37]
	v_pk_fma_f32 v[10:11], v[10:11], v[30:31], v[98:99]
	v_pk_fma_f32 v[12:13], v[12:13], v[28:29], v[100:101]
	v_pk_mul_f32 v[98:99], v[114:115], v[22:23]
	v_pk_fma_f32 v[12:13], v[68:69], v[32:33], v[12:13]
	v_pk_fma_f32 v[14:15], v[14:15], v[18:19], v[98:99]
	v_exp_f32_e32 v98, v12
	v_exp_f32_e32 v99, v13
	v_pk_fma_f32 v[10:11], v[70:71], v[34:35], v[10:11]
	v_pk_mul_f32 v[100:101], v[112:113], v[20:21]
	v_pk_fma_f32 v[14:15], v[78:79], v[26:27], v[14:15]
	v_pk_fma_f32 v[8:9], v[8:9], v[16:17], v[100:101]
	v_exp_f32_e32 v100, v10
	v_exp_f32_e32 v101, v11
	v_pk_add_f32 v[98:99], v[98:99], 1.0 op_sel_hi:[1,0]
	v_pk_fma_f32 v[8:9], v[76:77], v[24:25], v[8:9]
	v_rcp_f32_e32 v98, v98
	v_rcp_f32_e32 v99, v99
	v_pk_add_f32 v[100:101], v[100:101], 1.0 op_sel_hi:[1,0]
	v_mov_b32_dpp v106, v82 row_shl:1 row_mask:0xf bank_mask:0xf
	v_rcp_f32_e32 v100, v100
	v_rcp_f32_e32 v101, v101
	v_pk_mul_f32 v[12:13], v[12:13], v[98:99]
	v_mov_b32_dpp v107, v83 row_shl:1 row_mask:0xf bank_mask:0xf
	v_pk_mul_f32 v[8:9], v[8:9], v[12:13]
	v_pk_mul_f32 v[10:11], v[10:11], v[100:101]
	v_cvt_pk_bf16_f32 v98, v8, v9
	v_add_u32_e32 v8, 0x82, v208
	v_mad_i64_i32 v[8:9], s[2:3], v8, s22, v[110:111]
	v_pk_mul_f32 v[10:11], v[14:15], v[10:11]
	v_lshl_add_u64 v[8:9], v[8:9], 0, v[108:109]
	v_cvt_pk_bf16_f32 v99, v10, v11
	global_store_dwordx4 v[8:9], v[96:99], off nt
	v_pk_mul_f32 v[8:9], v[86:87], v[62:63]
	v_pk_mul_f32 v[10:11], v[84:85], v[60:61]
	v_pk_fma_f32 v[8:9], v[126:127], v[54:55], v[8:9]
	v_pk_fma_f32 v[10:11], v[124:125], v[52:53], v[10:11]
	v_pk_fma_f32 v[8:9], v[58:59], v[106:107], v[8:9]
	v_pk_fma_f32 v[10:11], v[56:57], v[104:105], v[10:11]
	v_pk_mul_f32 v[12:13], v[94:95], v[46:47]
	v_pk_mul_f32 v[14:15], v[92:93], v[44:45]
	v_pk_fma_f32 v[12:13], v[118:119], v[42:43], v[12:13]
	v_pk_fma_f32 v[14:15], v[116:117], v[40:41], v[14:15]
	v_exp_f32_e32 v40, v10
	v_exp_f32_e32 v41, v11
	v_exp_f32_e32 v42, v8
	v_exp_f32_e32 v43, v9
	v_mov_b32_dpp v128, v88 row_shl:1 row_mask:0xf bank_mask:0xf
	v_pk_add_f32 v[40:41], v[40:41], 1.0 op_sel_hi:[1,0]
	v_mov_b32_dpp v129, v89 row_shl:1 row_mask:0xf bank_mask:0xf
	v_pk_add_f32 v[42:43], v[42:43], 1.0 op_sel_hi:[1,0]
	v_rcp_f32_e32 v40, v40
	v_rcp_f32_e32 v41, v41
	v_rcp_f32_e32 v42, v42
	v_rcp_f32_e32 v43, v43
	v_mov_b32_dpp v130, v90 row_shl:1 row_mask:0xf bank_mask:0xf
	v_mov_b32_dpp v131, v91 row_shl:1 row_mask:0xf bank_mask:0xf
	v_pk_fma_f32 v[14:15], v[48:49], v[128:129], v[14:15]
	v_pk_fma_f32 v[12:13], v[50:51], v[130:131], v[12:13]
	v_pk_mul_f32 v[10:11], v[10:11], v[40:41]
	v_pk_mul_f32 v[8:9], v[8:9], v[42:43]
	v_mov_b32_dpp v4, v64 row_shl:1 row_mask:0xf bank_mask:0xf
	v_pk_mul_f32 v[12:13], v[12:13], v[8:9]
	v_pk_mul_f32 v[8:9], v[14:15], v[10:11]
	v_pk_mul_f32 v[10:11], v[70:71], v[38:39]
	v_cvt_pk_bf16_f32 v8, v8, v9
	v_cvt_pk_bf16_f32 v9, v12, v13
	v_pk_mul_f32 v[12:13], v[68:69], v[36:37]
	v_mov_b32_dpp v5, v65 row_shl:1 row_mask:0xf bank_mask:0xf
	v_mov_b32_dpp v6, v66 row_shl:1 row_mask:0xf bank_mask:0xf
	v_mov_b32_dpp v7, v67 row_shl:1 row_mask:0xf bank_mask:0xf
	v_pk_fma_f32 v[10:11], v[122:123], v[30:31], v[10:11]
	v_pk_fma_f32 v[12:13], v[120:121], v[28:29], v[12:13]
	v_pk_fma_f32 v[6:7], v[34:35], v[6:7], v[10:11]
	v_pk_fma_f32 v[4:5], v[32:33], v[4:5], v[12:13]
	v_pk_mul_f32 v[10:11], v[78:79], v[22:23]
	v_pk_mul_f32 v[12:13], v[76:77], v[20:21]
	v_mov_b32_dpp v0, v72 row_shl:1 row_mask:0xf bank_mask:0xf
	v_mov_b32_dpp v1, v73 row_shl:1 row_mask:0xf bank_mask:0xf
	v_mov_b32_dpp v2, v74 row_shl:1 row_mask:0xf bank_mask:0xf
	v_mov_b32_dpp v3, v75 row_shl:1 row_mask:0xf bank_mask:0xf
	v_pk_fma_f32 v[10:11], v[114:115], v[18:19], v[10:11]
	v_pk_fma_f32 v[12:13], v[112:113], v[16:17], v[12:13]
	v_pk_fma_f32 v[2:3], v[26:27], v[2:3], v[10:11]
	v_pk_fma_f32 v[0:1], v[24:25], v[0:1], v[12:13]
	v_exp_f32_e32 v10, v4
	v_exp_f32_e32 v11, v5
	v_exp_f32_e32 v12, v6
	v_exp_f32_e32 v13, v7
	s_movk_i32 s2, 0x7c
	v_pk_add_f32 v[10:11], v[10:11], 1.0 op_sel_hi:[1,0]
	v_cmp_ne_u32_e32 vcc, s2, v207
	v_pk_add_f32 v[12:13], v[12:13], 1.0 op_sel_hi:[1,0]
	v_rcp_f32_e32 v10, v10
	v_rcp_f32_e32 v11, v11
	v_rcp_f32_e32 v12, v12
	v_rcp_f32_e32 v13, v13
	v_pk_mul_f32 v[4:5], v[4:5], v[10:11]
	s_nop 0
	v_pk_mul_f32 v[0:1], v[0:1], v[4:5]
	v_pk_mul_f32 v[6:7], v[6:7], v[12:13]
	v_cvt_pk_bf16_f32 v10, v0, v1
	s_nop 0
	v_pk_mul_f32 v[2:3], v[2:3], v[6:7]
	s_nop 0
	v_cvt_pk_bf16_f32 v11, v2, v3
	s_and_saveexec_b64 s[2:3], vcc
	s_cbranch_execz .LBB0_1493
	v_add_u32_e32 v2, 0x83, v208
	v_mov_b64_e32 v[0:1], s[42:43]
	v_mad_i64_i32 v[0:1], s[8:9], v2, s22, v[0:1]
	v_lshl_add_u64 v[0:1], v[192:193], 1, v[0:1]
	global_store_dwordx4 v[0:1], v[8:11], off nt
